# r55 layout variant: layer-1 prep filler code (between M3 and M4) shifted by 4 bytes, later code by 8 (code alignment tuning)
# speedup vs baseline: 1.0018x; 1.0018x over previous
.LBB0_1080:
	s_andn2_b64 vcc, exec, s[34:35]
	s_cbranch_vccz .LBB0_1082
	s_mov_b32 s61, s39
	s_branch .LBB0_1009
	s_nop 0

.LBB0_1169:
	s_or_b64 exec, exec, s[0:1]
	v_readlane_b32 s0, v252, 31
	v_mov_b32_e32 v2, v182
	v_readlane_b32 s1, v252, 32
	s_barrier
	s_andn2_b64 vcc, exec, s[0:1]
	v_readfirstlane_b32 s10, v2
	s_mov_b32 s53, 0x7ffffc00
	s_cbranch_vccnz .LBB0_1210
	s_lshl_b32 s0, s10, 4
	s_ashr_i32 s18, s10, 7
	s_and_b32 s11, s10, 64
	s_and_b32 s19, s0, 0xfffffc00
	v_readlane_b32 s0, v252, 33
	v_readlane_b32 s52, v251, 16
	s_add_u32 s0, s48, s0
	v_readlane_b32 s56, v251, 20
	v_readlane_b32 s57, v251, 21
	s_addc_u32 s1, 0, 0
	v_readlane_b32 s58, v251, 22
	v_readlane_b32 s59, v251, 23
	v_readlane_b32 s60, v251, 24
	v_readlane_b32 s61, v251, 25
	v_readlane_b32 s62, v251, 26
	v_readlane_b32 s63, v251, 27
	v_readlane_b32 s64, v251, 28
	v_readlane_b32 s65, v251, 29
	v_readlane_b32 s66, v251, 30
	v_readlane_b32 s67, v251, 31
	s_mov_b64 s[20:21], s[56:57]
	s_lshl_b64 s[0:1], s[0:1], 11
	s_mov_b64 s[24:25], s[60:61]
	s_add_u32 s0, s24, s0
	s_addc_u32 s1, s25, s1
	s_add_u32 s8, s0, 0x400000
	s_addc_u32 s9, s1, 0
	s_add_u32 s4, s0, 0x400100
	s_addc_u32 s5, s1, 0
	s_add_u32 s6, s0, 0x400080
	s_addc_u32 s7, s1, 0
	s_add_u32 s0, s0, 0x400180
	v_readlane_b32 s2, v252, 35
	v_and_b32_e32 v1, 15, v2
	v_readlane_b32 s53, v251, 17
	v_readlane_b32 s54, v251, 18
	v_readlane_b32 s55, v251, 19
	s_addc_u32 s1, s1, 0
	s_add_i32 s12, s18, s2
	s_mov_b64 s[22:23], s[58:59]
	s_mov_b64 s[26:27], s[62:63]
	s_mov_b64 s[28:29], s[64:65]
	s_mov_b64 s[30:31], s[66:67]
	v_lshl_or_b32 v4, s12, 5, v1
	v_readlane_b32 s52, v253, 32
	v_ashrrev_i32_e32 v5, 31, v4
	v_readlane_b32 s53, v253, 33
	v_lshrrev_b32_e32 v3, 4, v2
	v_mov_b32_e32 v6, 0x2000
	v_lshl_add_u64 v[4:5], v[4:5], 2, s[52:53]
	global_load_dword v10, v[4:5], off
	global_load_dword v11, v[4:5], off offset:64
	global_load_dword v12, v[4:5], off offset:512
	global_load_dword v13, v[4:5], off offset:576
	v_bfe_u32 v50, v2, 4, 2
	v_lshrrev_b32_e32 v4, 1, v2
	v_bfe_u32 v5, v2, 1, 3
	v_lshl_add_u32 v6, v2, 4, v6
	v_ashrrev_i32_e32 v7, 3, v2
	v_xor_b32_e32 v2, v3, v2
	v_lshlrev_b32_e32 v2, 4, v2
	v_lshl_or_b32 v135, s18, 5, v1
	v_bitop3_b32 v4, v4, v50, 7 bitop3:0x6c
	v_bitop3_b32 v5, v50, v5, 4 bitop3:0x36
	v_or_b32_e32 v8, s11, v1
	v_ashrrev_i32_e32 v3, 7, v6
	v_and_b32_e32 v2, 0x70, v2
	v_readlane_b32 s2, v252, 42
	v_mov_b32_e32 v131, v0
	v_mov_b32_e32 v133, v0
	v_lshlrev_b32_e32 v51, 4, v4
	v_lshlrev_b32_e32 v53, 4, v5
	v_lshlrev_b32_e32 v4, 7, v135
	v_lshlrev_b32_e32 v5, 7, v8
	v_lshl_or_b32 v132, v3, 11, v2
	v_lshl_or_b32 v130, v7, 11, v2
	v_readlane_b32 s3, v252, 43
	v_or_b32_e32 v14, v4, v51
	v_or_b32_e32 v15, v53, v4
	v_or_b32_e32 v18, v51, v5
	v_or_b32_e32 v19, v53, v5
	v_lshl_or_b32 v134, v3, 9, v2
	v_lshl_or_b32 v136, v7, 9, v2
	v_lshl_add_u64 v[2:3], s[2:3], 0, v[130:131]
	v_lshl_add_u64 v[4:5], s[2:3], 0, v[132:133]
	s_mov_b64 s[12:13], 0x100
	v_lshl_add_u64 v[6:7], v[2:3], 0, s[70:71]
	v_lshl_add_u64 v[8:9], v[4:5], 0, s[70:71]
	v_lshl_add_u64 v[2:3], v[2:3], 0, s[12:13]
	v_lshl_add_u64 v[4:5], v[4:5], 0, s[12:13]
	s_and_b32 s12, s10, 0xffffff80
	s_add_i32 s12, s12, 0
	v_lshl_add_u32 v16, v1, 2, s12
	s_add_i32 s13, s19, 0
	v_add_u32_e32 v137, 0x24000, v16
	s_mov_b32 m0, s13
	v_add_u32_e32 v38, 0, v18
	v_add_u32_e32 v46, 0, v19
	v_readlane_b32 s60, v253, 40
	v_readlane_b32 s61, v253, 41
	v_lshlrev_b32_e32 v52, 3, v50
	s_waitcnt vmcnt(2)
	ds_write2_b32 v137, v10, v11 offset1:16
	s_waitcnt vmcnt(0)
	ds_write2_b32 v137, v12, v13 offset0:128 offset1:144
	global_load_lds_dwordx4 v130, s[2:3]
	s_add_i32 m0, s13, 0x2000
	v_mov_b32_e32 v50, 0
	global_load_lds_dwordx4 v132, s[2:3]
	v_readlane_b32 s2, v252, 36
	s_add_i32 m0, s13, 0x4000
	v_readlane_b32 s3, v252, 37
	v_readlane_b32 s39, v252, 34
	s_mov_b32 s20, 1
	s_mov_b32 s30, 3
	s_mov_b32 s21, 2
	v_or_b32_e32 v140, s11, v52
	global_load_lds_dwordx4 v130, s[2:3]
	s_add_i32 m0, s13, 0x6000
	v_lshl_add_u32 v141, v1, 7, 0
	global_load_lds_dwordx4 v132, s[2:3]
	s_add_i32 m0, s13, 0x8000
	v_readlane_b32 s2, v252, 38
	global_load_lds_dwordx4 v130, s[8:9]
	s_add_i32 m0, s13, 0xa000
	v_readlane_b32 s3, v252, 39
	global_load_lds_dwordx4 v132, s[8:9]
	s_add_i32 m0, s13, 0xc000
	v_readlane_b32 s8, v252, 44
	global_load_lds_dwordx4 v[6:7], off
	s_add_i32 m0, s13, 0xe000
	v_add_u32_e32 v6, 0, v14
	global_load_lds_dwordx4 v[8:9], off
	s_add_i32 m0, s13, 0x10000
	v_add_u32_e32 v14, 0, v15
	global_load_lds_dwordx4 v130, s[2:3]
	s_add_i32 m0, s13, 0x12000
	s_mov_b32 s34, 16
	global_load_lds_dwordx4 v132, s[2:3]
	s_add_i32 m0, s13, 0x14000
	v_readlane_b32 s2, v252, 40
	global_load_lds_dwordx4 v130, s[6:7]
	s_add_i32 m0, s13, 0x16000
	v_readlane_b32 s3, v252, 41
	global_load_lds_dwordx4 v132, s[6:7]
	s_add_i32 m0, s13, 0x18000
	s_mov_b32 s29, 0
	global_load_lds_dwordx4 v[2:3], off
	s_add_i32 m0, s13, 0x1a000
	v_mov_b32_e32 v154, 0
	global_load_lds_dwordx4 v[4:5], off
	s_add_i32 m0, s13, 0x1c000
	v_mov_b32_e32 v195, 0
	global_load_lds_dwordx4 v130, s[2:3]
	s_add_i32 m0, s13, 0x1e000
	v_mov_b32_e32 v156, 0
	global_load_lds_dwordx4 v132, s[2:3]
	s_add_i32 m0, s13, 0x20000
	v_mov_b32_e32 v157, 0
	global_load_lds_dwordx4 v130, s[4:5]
	s_add_i32 m0, s13, 0x22000
	v_mov_b32_e32 v158, 0
	global_load_lds_dwordx4 v132, s[4:5]
	s_waitcnt vmcnt(12)
	s_barrier
	ds_read_b128 v[2:5], v6
	ds_read_b128 v[6:9], v6 offset:2048
	ds_read_b128 v[10:13], v14
	ds_read_b128 v[14:17], v14 offset:2048
	ds_read_b128 v[18:21], v38 offset:32768
	ds_read_b128 v[26:29], v38 offset:34816
	ds_read_b128 v[22:25], v46 offset:32768
	ds_read_b128 v[30:33], v46 offset:34816
	ds_read_b128 v[34:37], v38 offset:36864
	ds_read_b128 v[38:41], v38 offset:38912
	ds_read_b128 v[42:45], v46 offset:36864
	ds_read_b128 v[46:49], v46 offset:38912
	s_lshl_b32 s4, s11, 1
	s_add_u32 s22, s60, s4
	s_addc_u32 s23, s61, 0
	s_lshl_b32 s4, s18, 12
	s_add_i32 s5, s4, 0xc000
	v_or_b32_e32 v142, s5, v51
	v_or_b32_e32 v144, s5, v53
	s_lshl_b32 s5, s10, 7
	s_add_i32 s6, s4, 0xc800
	s_and_b32 s5, s5, 0x2000
	v_or_b32_e32 v143, s6, v51
	v_or_b32_e32 v145, s6, v53
	s_or_b32 s6, s5, 0x14800
	s_or_b32 s7, s5, 0x15000
	s_or_b32 s5, s5, 0x14000
	v_or_b32_e32 v146, s6, v53
	v_or_b32_e32 v147, s7, v53
	v_or_b32_e32 v148, s5, v53
	v_or_b32_e32 v149, s6, v51
	v_or_b32_e32 v150, s7, v51
	s_add_i32 s24, s19, 0x2000
	v_or_b32_e32 v151, s5, v51
	v_or_b32_e32 v152, s4, v53
	v_or_b32_e32 v153, s4, v51
	s_add_i32 s25, s19, 0x8000
	s_add_i32 s26, s19, 0x4000
	s_add_i32 s27, s19, 0xa000
	s_add_i32 s28, s19, 0x6000
	s_mov_b64 s[10:11], -1
	s_mov_b64 s[4:5], 0
	v_mov_b32_e32 v159, 0
	v_mov_b32_e32 v160, 0
	v_mov_b32_e32 v161, 0
	v_mov_b32_e32 v166, 0
	v_mov_b32_e32 v167, 0
	v_mov_b32_e32 v168, 0
	v_mov_b32_e32 v169, 0
	v_mov_b32_e32 v170, 0
	v_mov_b32_e32 v171, 0
	v_mov_b32_e32 v172, 0
	v_mov_b32_e32 v173, 0
	v_mov_b32_e32 v174, 0
	v_mov_b32_e32 v175, 0
	v_mov_b32_e32 v176, 0
	v_mov_b32_e32 v177, 0
	v_mov_b32_e32 v178, 0
	v_mov_b32_e32 v179, 0
	v_mov_b32_e32 v180, 0
	v_mov_b32_e32 v181, 0
	v_mov_b32_e32 v197, 0
	v_mov_b32_e32 v198, 0
	v_mov_b32_e32 v199, 0
	v_mov_b32_e32 v200, 0
	v_mov_b32_e32 v201, 0
	v_mov_b32_e32 v202, 0
	v_mov_b32_e32 v203, 0
	v_mov_b32_e32 v204, 0
	v_mov_b32_e32 v206, 0
	v_mov_b32_e32 v205, 0
	v_mov_b32_e32 v208, 0
	v_mov_b32_e32 v207, 0
	v_mov_b32_e32 v210, 0
	v_mov_b32_e32 v209, 0
	v_mov_b32_e32 v212, 0
	v_mov_b32_e32 v211, 0
	v_mov_b32_e32 v214, 0
	v_mov_b32_e32 v213, 0
	v_mov_b32_e32 v216, 0
	v_mov_b32_e32 v215, 0
	v_mov_b32_e32 v218, 0
	v_mov_b32_e32 v217, 0
	v_mov_b32_e32 v220, 0
	v_mov_b32_e32 v219, 0
	v_mov_b32_e32 v222, 0
	v_mov_b32_e32 v221, 0
	v_mov_b32_e32 v224, 0
	v_mov_b32_e32 v223, 0
	v_mov_b32_e32 v226, 0
	v_mov_b32_e32 v225, 0
	v_mov_b32_e32 v228, 0
	v_mov_b32_e32 v227, 0
	v_mov_b32_e32 v230, 0
	v_mov_b32_e32 v229, 0
	v_mov_b32_e32 v232, 0
	v_mov_b32_e32 v231, 0
	v_mov_b32_e32 v234, 0
	v_mov_b32_e32 v233, 0
	v_mov_b32_e32 v236, 0
	v_mov_b32_e32 v235, 0
	v_lshlrev_b32_e32 v138, 1, v52
	s_mov_b32 s43, 0
	s_mov_b32 s31, s39
	s_mov_b32 s44, 0
	s_mov_b32 s17, 3
	s_mov_b32 s41, 0
	s_mov_b32 s42, 0
	s_mov_b32 s40, 0
	v_readlane_b32 s9, v252, 45
	s_mov_b64 s[14:15], 0
	s_mov_b32 s35, 0
	s_mov_b64 s[6:7], 0
	s_mov_b32 s37, 16
	s_mov_b32 s36, 0
	s_mov_b32 s38, 0
	v_mov_b32_e32 v51, v50
	v_mov_b32_e32 v52, v50
	v_mov_b32_e32 v53, v50
	v_mov_b32_e32 v54, v50
	v_mov_b32_e32 v55, v50
	v_mov_b32_e32 v56, v50
	v_mov_b32_e32 v57, v50
	v_mov_b32_e32 v58, v50
	v_mov_b32_e32 v59, v50
	v_mov_b32_e32 v60, v50
	v_mov_b32_e32 v61, v50
	v_mov_b32_e32 v62, v50
	v_mov_b32_e32 v63, v50
	v_mov_b32_e32 v64, v50
	v_mov_b32_e32 v65, v50
	v_mov_b32_e32 v66, v50
	v_mov_b32_e32 v67, v50
	v_mov_b32_e32 v68, v50
	v_mov_b32_e32 v69, v50
	v_mov_b32_e32 v70, v50
	v_mov_b32_e32 v71, v50
	v_mov_b32_e32 v72, v50
	v_mov_b32_e32 v73, v50
	v_mov_b32_e32 v74, v50
	v_mov_b32_e32 v75, v50
	v_mov_b32_e32 v76, v50
	v_mov_b32_e32 v77, v50
	v_mov_b32_e32 v78, v50
	v_mov_b32_e32 v79, v50
	v_mov_b32_e32 v80, v50
	v_mov_b32_e32 v81, v50
	v_mov_b32_e32 v82, v50
	v_mov_b32_e32 v83, v50
	v_mov_b32_e32 v84, v50
	v_mov_b32_e32 v85, v50
	v_mov_b32_e32 v86, v50
	v_mov_b32_e32 v87, v50
	v_mov_b32_e32 v88, v50
	v_mov_b32_e32 v89, v50
	v_mov_b32_e32 v90, v50
	v_mov_b32_e32 v91, v50
	v_mov_b32_e32 v92, v50
	v_mov_b32_e32 v93, v50
	v_mov_b32_e32 v94, v50
	v_mov_b32_e32 v95, v50
	v_mov_b32_e32 v96, v50
	v_mov_b32_e32 v97, v50
	v_mov_b32_e32 v98, v50
	v_mov_b32_e32 v99, v50
	v_mov_b32_e32 v100, v50
	v_mov_b32_e32 v101, v50
	v_mov_b32_e32 v102, v50
	v_mov_b32_e32 v103, v50
	v_mov_b32_e32 v104, v50
	v_mov_b32_e32 v105, v50
	v_mov_b32_e32 v106, v50
	v_mov_b32_e32 v107, v50
	v_mov_b32_e32 v108, v50
	v_mov_b32_e32 v109, v50
	v_mov_b32_e32 v110, v50
	v_mov_b32_e32 v111, v50
	v_mov_b32_e32 v112, v50
	v_mov_b32_e32 v113, v50
	v_readlane_b32 s54, v253, 34
	v_readlane_b32 s55, v253, 35
	v_readlane_b32 s56, v253, 36
	v_readlane_b32 s57, v253, 37
	v_readlane_b32 s58, v253, 38
	v_readlane_b32 s59, v253, 39
	v_readlane_b32 s62, v253, 42
	v_readlane_b32 s63, v253, 43
	v_readlane_b32 s64, v253, 44
	v_readlane_b32 s65, v253, 45
	v_readlane_b32 s66, v253, 46
	v_readlane_b32 s67, v253, 47
	s_branch .LBB0_1173
	s_nop 0
